# P13 mamba chunk loop: LDS fragment reads for the G, Y2 and state-update MFMA stages issued several MFMAs ahead into spare VGPRs (same MFMAs and order)
# speedup vs baseline: 1.0630x; 1.0135x over previous
.LBB0_2452:
	s_or_b64 exec, exec, s[92:93]
	ds_read_b32 v66, v210
	s_add_i32 s3, s3, 64
	s_and_b64 vcc, exec, s[88:89]
	s_waitcnt lgkmcnt(0)
	v_mul_f32_e32 v66, 0x3fb8aa3b, v66
	v_exp_f32_e32 v82, v66
	ds_read_b128 v[234:237], v212 offset:34816
	ds_read_b128 v[66:69], v164 offset:62464
	ds_read_b128 v[238:241], v212 offset:34848
	ds_read_b128 v[70:73], v164 offset:62496
	ds_read_b128 v[246:249], v212 offset:34880
	ds_read_b128 v[74:77], v164 offset:62528
	ds_read_b128 v[250:253], v212 offset:34912
	ds_read_b128 v[78:81], v164 offset:62560
	ds_read_b128 v[84:87], v212 offset:39424
	v_pk_mul_f32 v[64:65], v[64:65], v[82:83] op_sel_hi:[1,0]
	v_pk_mul_f32 v[62:63], v[62:63], v[82:83] op_sel_hi:[1,0]
	v_pk_mul_f32 v[60:61], v[60:61], v[82:83] op_sel_hi:[1,0]
	v_pk_mul_f32 v[58:59], v[58:59], v[82:83] op_sel_hi:[1,0]
	v_pk_mul_f32 v[56:57], v[56:57], v[82:83] op_sel_hi:[1,0]
	v_pk_mul_f32 v[54:55], v[54:55], v[82:83] op_sel_hi:[1,0]
	v_pk_mul_f32 v[52:53], v[52:53], v[82:83] op_sel_hi:[1,0]
	v_pk_mul_f32 v[50:51], v[50:51], v[82:83] op_sel_hi:[1,0]
	v_pk_mul_f32 v[48:49], v[48:49], v[82:83] op_sel_hi:[1,0]
	v_pk_mul_f32 v[46:47], v[46:47], v[82:83] op_sel_hi:[1,0]
	s_waitcnt lgkmcnt(7)
	v_mfma_f32_32x32x16_bf16 v[50:65], v[234:237], v[66:69], v[50:65]
	ds_read_b128 v[234:237], v212 offset:39456
	v_mul_f32_e64 v44, v44, v82
	v_mul_f32_e64 v45, v45, v82
	v_mul_f32_e64 v42, v42, v82
	v_mul_f32_e64 v43, v43, v82
	v_mul_f32_e64 v40, v40, v82
	v_mul_f32_e64 v41, v41, v82
	v_pk_mul_f32 v[38:39], v[38:39], v[82:83] op_sel_hi:[1,0]
	v_pk_mul_f32 v[36:37], v[36:37], v[82:83] op_sel_hi:[1,0]
	v_pk_mul_f32 v[34:35], v[34:35], v[82:83] op_sel_hi:[1,0]
	v_pk_mul_f32 v[32:33], v[32:33], v[82:83] op_sel_hi:[1,0]
	s_waitcnt lgkmcnt(6)
	v_mfma_f32_32x32x16_bf16 v[50:65], v[238:241], v[70:73], v[50:65]
	ds_read_b128 v[238:241], v212 offset:39488
	v_mul_f32_e64 v30, v30, v82
	v_mul_f32_e64 v31, v31, v82
	v_mul_f32_e64 v28, v28, v82
	v_mul_f32_e64 v29, v29, v82
	v_pk_mul_f32 v[26:27], v[26:27], v[82:83] op_sel_hi:[1,0]
	v_pk_mul_f32 v[24:25], v[24:25], v[82:83] op_sel_hi:[1,0]
	v_pk_mul_f32 v[22:23], v[22:23], v[82:83] op_sel_hi:[1,0]
	v_pk_mul_f32 v[20:21], v[20:21], v[82:83] op_sel_hi:[1,0]
	s_waitcnt lgkmcnt(5)
	v_mfma_f32_32x32x16_bf16 v[50:65], v[246:249], v[74:77], v[50:65]
	ds_read_b128 v[246:249], v212 offset:39520
	v_mul_f32_e64 v18, v18, v82
	v_mul_f32_e64 v19, v19, v82
	v_mul_f32_e64 v16, v16, v82
	v_mul_f32_e64 v17, v17, v82
	v_pk_mul_f32 v[14:15], v[14:15], v[82:83] op_sel_hi:[1,0]
	v_pk_mul_f32 v[12:13], v[12:13], v[82:83] op_sel_hi:[1,0]
	v_pk_mul_f32 v[10:11], v[10:11], v[82:83] op_sel_hi:[1,0]
	v_pk_mul_f32 v[8:9], v[8:9], v[82:83] op_sel_hi:[1,0]
	s_waitcnt lgkmcnt(4)
	v_mfma_f32_32x32x16_bf16 v[50:65], v[250:253], v[78:81], v[50:65]
	ds_read_b128 v[250:253], v212 offset:44032
	v_mul_f32_e64 v6, v6, v82
	v_mul_f32_e64 v7, v7, v82
	v_mul_f32_e64 v4, v4, v82
	v_mul_f32_e64 v5, v5, v82
	v_pk_mul_f32 v[2:3], v[2:3], v[82:83] op_sel_hi:[1,0]
	s_waitcnt lgkmcnt(4)
	v_mfma_f32_32x32x16_bf16 v[34:49], v[84:87], v[66:69], v[34:49]
	ds_read_b128 v[84:87], v212 offset:44064
	s_waitcnt lgkmcnt(4)
	v_mfma_f32_32x32x16_bf16 v[34:49], v[234:237], v[70:73], v[34:49]
	ds_read_b128 v[234:237], v212 offset:44096
	s_waitcnt lgkmcnt(4)
	v_mfma_f32_32x32x16_bf16 v[34:49], v[238:241], v[74:77], v[34:49]
	ds_read_b128 v[238:241], v212 offset:44128
	s_waitcnt lgkmcnt(4)
	v_mfma_f32_32x32x16_bf16 v[34:49], v[246:249], v[78:81], v[34:49]
	ds_read_b128 v[246:249], v212 offset:48640
	s_waitcnt lgkmcnt(4)
	v_mfma_f32_32x32x16_bf16 v[18:33], v[250:253], v[66:69], v[18:33]
	ds_read_b128 v[250:253], v212 offset:48672
	s_waitcnt lgkmcnt(4)
	v_mfma_f32_32x32x16_bf16 v[18:33], v[84:87], v[70:73], v[18:33]
	ds_read_b128 v[84:87], v212 offset:48704
	s_waitcnt lgkmcnt(4)
	v_mfma_f32_32x32x16_bf16 v[18:33], v[234:237], v[74:77], v[18:33]
	ds_read_b128 v[234:237], v212 offset:48736
	s_waitcnt lgkmcnt(4)
	v_mfma_f32_32x32x16_bf16 v[18:33], v[238:241], v[78:81], v[18:33]
	s_waitcnt lgkmcnt(3)
	v_mfma_f32_32x32x16_bf16 v[2:17], v[246:249], v[66:69], v[2:17]
	s_waitcnt lgkmcnt(2)
	v_mfma_f32_32x32x16_bf16 v[2:17], v[250:253], v[70:73], v[2:17]
	s_waitcnt lgkmcnt(1)
	v_mfma_f32_32x32x16_bf16 v[2:17], v[84:87], v[74:77], v[2:17]
	s_waitcnt lgkmcnt(0)
	s_barrier
	v_mfma_f32_32x32x16_bf16 v[2:17], v[234:237], v[78:81], v[2:17]
	s_cbranch_vccnz .LBB0_2529

.LBB0_2473:
	v_mov_b32_e32 v82, 0
	v_mov_b32_e32 v83, 0
	v_mov_b32_e32 v84, 0
	v_mov_b32_e32 v85, 0
	v_mov_b32_e32 v86, 0
	v_mov_b32_e32 v87, 0
	v_mov_b32_e32 v88, 0
	v_mov_b32_e32 v89, 0
	v_mov_b32_e32 v90, 0
	v_mov_b32_e32 v91, 0
	v_mov_b32_e32 v92, 0
	v_mov_b32_e32 v93, 0
	v_mov_b32_e32 v94, 0
	v_mov_b32_e32 v95, 0
	v_mov_b32_e32 v96, 0
	v_mov_b32_e32 v97, 0
	s_and_saveexec_b64 s[92:93], s[24:25]
	s_cbranch_execz .LBB0_2475
	v_add_u32_e32 v74, v162, v161
	ds_read_b128 v[66:69], v74
	ds_read_b128 v[70:73], v168 offset:17408
	ds_read_b128 v[234:237], v74 offset:32
	ds_read_b128 v[238:241], v168 offset:17440
	ds_read_b128 v[246:249], v74 offset:64
	ds_read_b128 v[250:253], v168 offset:17472
	s_waitcnt lgkmcnt(4)
	v_mfma_f32_32x32x16_bf16 v[82:97], v[66:69], v[70:73], 0
	ds_read_b128 v[66:69], v74 offset:96
	ds_read_b128 v[70:73], v168 offset:17504
	s_waitcnt lgkmcnt(4)
	v_mfma_f32_32x32x16_bf16 v[82:97], v[234:237], v[238:241], v[82:97]
	ds_read_b128 v[234:237], v74 offset:128
	ds_read_b128 v[238:241], v168 offset:17536
	s_waitcnt lgkmcnt(4)
	v_mfma_f32_32x32x16_bf16 v[82:97], v[246:249], v[250:253], v[82:97]
	ds_read_b128 v[246:249], v74 offset:160
	ds_read_b128 v[250:253], v168 offset:17568
	s_waitcnt lgkmcnt(4)
	v_mfma_f32_32x32x16_bf16 v[82:97], v[66:69], v[70:73], v[82:97]
	ds_read_b128 v[66:69], v74 offset:192
	ds_read_b128 v[70:73], v168 offset:17600
	s_waitcnt lgkmcnt(4)
	v_mfma_f32_32x32x16_bf16 v[82:97], v[234:237], v[238:241], v[82:97]
	ds_read_b128 v[234:237], v74 offset:224
	ds_read_b128 v[238:241], v168 offset:17632
	s_waitcnt lgkmcnt(4)
	v_mfma_f32_32x32x16_bf16 v[82:97], v[246:249], v[250:253], v[82:97]
	s_waitcnt lgkmcnt(2)
	v_mfma_f32_32x32x16_bf16 v[82:97], v[66:69], v[70:73], v[82:97]
	s_waitcnt lgkmcnt(0)
	v_mfma_f32_32x32x16_bf16 v[82:97], v[234:237], v[238:241], v[82:97]
.LBB0_2475:
	s_or_b64 exec, exec, s[92:93]
	ds_read2_b64 v[66:69], v162 offset1:2
	v_cvt_pk_bf16_f32 v70, v50, v51
	v_cvt_pk_bf16_f32 v71, v52, v53
	v_cvt_pk_bf16_f32 v72, v54, v55
	v_cvt_pk_bf16_f32 v73, v56, v57
	ds_read2_b64 v[226:229], v162 offset0:4 offset1:6
	ds_read2_b64 v[234:237], v162 offset0:8 offset1:10
	ds_read2_b64 v[238:241], v162 offset0:12 offset1:14
	ds_read2_b64 v[246:249], v162 offset0:16 offset1:18
	v_cvt_pk_bf16_f32 v230, v58, v59
	v_cvt_pk_bf16_f32 v231, v60, v61
	v_cvt_pk_bf16_f32 v232, v62, v63
	s_waitcnt lgkmcnt(4)
	v_mfma_f32_32x32x16_bf16 v[66:81], v[66:69], v[70:73], 0
	v_cvt_pk_bf16_f32 v233, v64, v65
	s_waitcnt lgkmcnt(3)
	s_nop 0
	v_mfma_f32_32x32x16_bf16 v[66:81], v[226:229], v[230:233], v[66:81]
	ds_read2_b64 v[226:229], v162 offset0:20 offset1:22
	v_cvt_pk_bf16_f32 v230, v34, v35
	v_cvt_pk_bf16_f32 v231, v36, v37
	v_cvt_pk_bf16_f32 v232, v38, v39
	v_cvt_pk_bf16_f32 v233, v40, v41
	s_waitcnt lgkmcnt(3)
	s_nop 0
	v_mfma_f32_32x32x16_bf16 v[66:81], v[234:237], v[230:233], v[66:81]
	ds_read2_b64 v[234:237], v162 offset0:24 offset1:26
	v_cvt_pk_bf16_f32 v230, v42, v43
	v_cvt_pk_bf16_f32 v231, v44, v45
	v_cvt_pk_bf16_f32 v232, v46, v47
	v_cvt_pk_bf16_f32 v233, v48, v49
	s_waitcnt lgkmcnt(3)
	s_nop 0
	v_mfma_f32_32x32x16_bf16 v[66:81], v[238:241], v[230:233], v[66:81]
	ds_read2_b64 v[238:241], v162 offset0:28 offset1:30
	v_cvt_pk_bf16_f32 v230, v18, v19
	v_cvt_pk_bf16_f32 v231, v20, v21
	v_cvt_pk_bf16_f32 v232, v22, v23
	v_cvt_pk_bf16_f32 v233, v24, v25
	s_waitcnt lgkmcnt(3)
	s_nop 0
	v_mfma_f32_32x32x16_bf16 v[66:81], v[246:249], v[230:233], v[66:81]
	v_cvt_pk_bf16_f32 v230, v26, v27
	v_cvt_pk_bf16_f32 v231, v28, v29
	v_cvt_pk_bf16_f32 v232, v30, v31
	v_cvt_pk_bf16_f32 v233, v32, v33
	s_waitcnt lgkmcnt(2)
	s_nop 0
	v_mfma_f32_32x32x16_bf16 v[66:81], v[226:229], v[230:233], v[66:81]
	v_cvt_pk_bf16_f32 v230, v2, v3
	v_cvt_pk_bf16_f32 v231, v4, v5
	v_cvt_pk_bf16_f32 v232, v6, v7
	v_cvt_pk_bf16_f32 v233, v8, v9
	s_waitcnt lgkmcnt(1)
	s_nop 0
	v_mfma_f32_32x32x16_bf16 v[66:81], v[234:237], v[230:233], v[66:81]
	v_cvt_pk_bf16_f32 v230, v10, v11
	v_cvt_pk_bf16_f32 v231, v12, v13
	v_cvt_pk_bf16_f32 v232, v14, v15
	v_cvt_pk_bf16_f32 v233, v16, v17
	s_waitcnt lgkmcnt(0)
	s_barrier
	v_mfma_f32_32x32x16_bf16 v[66:81], v[238:241], v[230:233], v[66:81]
	s_and_saveexec_b64 s[92:93], s[24:25]
	s_xor_b64 vcc, exec, s[92:93]
	s_cbranch_execz .LBB0_2509
	ds_read_b32 v147, v169
	ds_read_b32 v139, v170
	v_mov_b32_e32 v151, 0
	v_mov_b32_e32 v155, 0
	s_and_saveexec_b64 s[92:93], s[10:11]
	s_cbranch_execz .LBB0_2478
	ds_read_b32 v155, v181
	s_waitcnt lgkmcnt(0)
	v_sub_f32_e32 v155, v155, v147
	v_mul_f32_e32 v155, 0x3fb8aa3b, v155
	v_exp_f32_e32 v155, v155
	s_nop 0
	v_mul_f32_e32 v82, v82, v155
	v_mul_f32_e32 v155, v139, v82

.LBB0_2665:
	s_or_b64 exec, exec, s[92:93]
	ds_read_b32 v66, v206
	s_add_i32 s96, s96, 64
	s_and_b64 vcc, exec, s[90:91]
	s_waitcnt lgkmcnt(0)
	v_mul_f32_e32 v66, 0x3fb8aa3b, v66
	v_exp_f32_e32 v82, v66
	ds_read_b128 v[234:237], v208 offset:34816
	ds_read_b128 v[66:69], v159 offset:62464
	ds_read_b128 v[238:241], v208 offset:34848
	ds_read_b128 v[70:73], v159 offset:62496
	ds_read_b128 v[246:249], v208 offset:34880
	ds_read_b128 v[74:77], v159 offset:62528
	ds_read_b128 v[250:253], v208 offset:34912
	ds_read_b128 v[78:81], v159 offset:62560
	ds_read_b128 v[84:87], v208 offset:39424
	v_pk_mul_f32 v[64:65], v[64:65], v[82:83] op_sel_hi:[1,0]
	v_pk_mul_f32 v[62:63], v[62:63], v[82:83] op_sel_hi:[1,0]
	v_pk_mul_f32 v[60:61], v[60:61], v[82:83] op_sel_hi:[1,0]
	v_pk_mul_f32 v[58:59], v[58:59], v[82:83] op_sel_hi:[1,0]
	v_pk_mul_f32 v[56:57], v[56:57], v[82:83] op_sel_hi:[1,0]
	v_pk_mul_f32 v[54:55], v[54:55], v[82:83] op_sel_hi:[1,0]
	v_pk_mul_f32 v[52:53], v[52:53], v[82:83] op_sel_hi:[1,0]
	v_pk_mul_f32 v[50:51], v[50:51], v[82:83] op_sel_hi:[1,0]
	v_pk_mul_f32 v[48:49], v[48:49], v[82:83] op_sel_hi:[1,0]
	v_pk_mul_f32 v[46:47], v[46:47], v[82:83] op_sel_hi:[1,0]
	s_waitcnt lgkmcnt(7)
	v_mfma_f32_32x32x16_bf16 v[50:65], v[234:237], v[66:69], v[50:65]
	ds_read_b128 v[234:237], v208 offset:39456
	v_mul_f32_e64 v44, v44, v82
	v_mul_f32_e64 v45, v45, v82
	v_mul_f32_e64 v42, v42, v82
	v_mul_f32_e64 v43, v43, v82
	v_mul_f32_e64 v40, v40, v82
	v_mul_f32_e64 v41, v41, v82
	v_pk_mul_f32 v[38:39], v[38:39], v[82:83] op_sel_hi:[1,0]
	v_pk_mul_f32 v[36:37], v[36:37], v[82:83] op_sel_hi:[1,0]
	v_pk_mul_f32 v[34:35], v[34:35], v[82:83] op_sel_hi:[1,0]
	v_pk_mul_f32 v[32:33], v[32:33], v[82:83] op_sel_hi:[1,0]
	s_waitcnt lgkmcnt(6)
	v_mfma_f32_32x32x16_bf16 v[50:65], v[238:241], v[70:73], v[50:65]
	ds_read_b128 v[238:241], v208 offset:39488
	v_mul_f32_e64 v30, v30, v82
	v_mul_f32_e64 v31, v31, v82
	v_mul_f32_e64 v28, v28, v82
	v_mul_f32_e64 v29, v29, v82
	v_pk_mul_f32 v[26:27], v[26:27], v[82:83] op_sel_hi:[1,0]
	v_pk_mul_f32 v[24:25], v[24:25], v[82:83] op_sel_hi:[1,0]
	v_pk_mul_f32 v[22:23], v[22:23], v[82:83] op_sel_hi:[1,0]
	v_pk_mul_f32 v[20:21], v[20:21], v[82:83] op_sel_hi:[1,0]
	s_waitcnt lgkmcnt(5)
	v_mfma_f32_32x32x16_bf16 v[50:65], v[246:249], v[74:77], v[50:65]
	ds_read_b128 v[246:249], v208 offset:39520
	v_mul_f32_e64 v18, v18, v82
	v_mul_f32_e64 v19, v19, v82
	v_mul_f32_e64 v16, v16, v82
	v_mul_f32_e64 v17, v17, v82
	v_pk_mul_f32 v[14:15], v[14:15], v[82:83] op_sel_hi:[1,0]
	v_pk_mul_f32 v[12:13], v[12:13], v[82:83] op_sel_hi:[1,0]
	v_pk_mul_f32 v[10:11], v[10:11], v[82:83] op_sel_hi:[1,0]
	v_pk_mul_f32 v[8:9], v[8:9], v[82:83] op_sel_hi:[1,0]
	s_waitcnt lgkmcnt(4)
	v_mfma_f32_32x32x16_bf16 v[50:65], v[250:253], v[78:81], v[50:65]
	ds_read_b128 v[250:253], v208 offset:44032
	v_mul_f32_e64 v6, v6, v82
	v_mul_f32_e64 v7, v7, v82
	v_mul_f32_e64 v4, v4, v82
	v_mul_f32_e64 v5, v5, v82
	v_pk_mul_f32 v[2:3], v[2:3], v[82:83] op_sel_hi:[1,0]
	s_waitcnt lgkmcnt(4)
	v_mfma_f32_32x32x16_bf16 v[34:49], v[84:87], v[66:69], v[34:49]
	ds_read_b128 v[84:87], v208 offset:44064
	s_waitcnt lgkmcnt(4)
	v_mfma_f32_32x32x16_bf16 v[34:49], v[234:237], v[70:73], v[34:49]
	ds_read_b128 v[234:237], v208 offset:44096
	s_waitcnt lgkmcnt(4)
	v_mfma_f32_32x32x16_bf16 v[34:49], v[238:241], v[74:77], v[34:49]
	ds_read_b128 v[238:241], v208 offset:44128
	s_waitcnt lgkmcnt(4)
	v_mfma_f32_32x32x16_bf16 v[34:49], v[246:249], v[78:81], v[34:49]
	ds_read_b128 v[246:249], v208 offset:48640
	s_waitcnt lgkmcnt(4)
	v_mfma_f32_32x32x16_bf16 v[18:33], v[250:253], v[66:69], v[18:33]
	ds_read_b128 v[250:253], v208 offset:48672
	s_waitcnt lgkmcnt(4)
	v_mfma_f32_32x32x16_bf16 v[18:33], v[84:87], v[70:73], v[18:33]
	ds_read_b128 v[84:87], v208 offset:48704
	s_waitcnt lgkmcnt(4)
	v_mfma_f32_32x32x16_bf16 v[18:33], v[234:237], v[74:77], v[18:33]
	ds_read_b128 v[234:237], v208 offset:48736
	s_waitcnt lgkmcnt(4)
	v_mfma_f32_32x32x16_bf16 v[18:33], v[238:241], v[78:81], v[18:33]
	s_waitcnt lgkmcnt(3)
	v_mfma_f32_32x32x16_bf16 v[2:17], v[246:249], v[66:69], v[2:17]
	s_waitcnt lgkmcnt(2)
	v_mfma_f32_32x32x16_bf16 v[2:17], v[250:253], v[70:73], v[2:17]
	s_waitcnt lgkmcnt(1)
	v_mfma_f32_32x32x16_bf16 v[2:17], v[84:87], v[74:77], v[2:17]
	s_waitcnt lgkmcnt(0)
	s_barrier
	v_mfma_f32_32x32x16_bf16 v[2:17], v[234:237], v[78:81], v[2:17]
	s_cbranch_vccnz .LBB0_2742

.LBB0_2686:
	v_mov_b32_e32 v82, 0
	v_mov_b32_e32 v83, 0
	v_mov_b32_e32 v84, 0
	v_mov_b32_e32 v85, 0
	v_mov_b32_e32 v86, 0
	v_mov_b32_e32 v87, 0
	v_mov_b32_e32 v88, 0
	v_mov_b32_e32 v89, 0
	v_mov_b32_e32 v90, 0
	v_mov_b32_e32 v91, 0
	v_mov_b32_e32 v92, 0
	v_mov_b32_e32 v93, 0
	v_mov_b32_e32 v94, 0
	v_mov_b32_e32 v95, 0
	v_mov_b32_e32 v96, 0
	v_mov_b32_e32 v97, 0
	s_and_saveexec_b64 s[92:93], s[4:5]
	s_cbranch_execz .LBB0_2688
	v_add_u32_e32 v74, v157, v156
	ds_read_b128 v[66:69], v74
	ds_read_b128 v[70:73], v162 offset:17408
	ds_read_b128 v[234:237], v74 offset:32
	ds_read_b128 v[238:241], v162 offset:17440
	ds_read_b128 v[246:249], v74 offset:64
	ds_read_b128 v[250:253], v162 offset:17472
	s_waitcnt lgkmcnt(4)
	v_mfma_f32_32x32x16_bf16 v[82:97], v[66:69], v[70:73], 0
	ds_read_b128 v[66:69], v74 offset:96
	ds_read_b128 v[70:73], v162 offset:17504
	s_waitcnt lgkmcnt(4)
	v_mfma_f32_32x32x16_bf16 v[82:97], v[234:237], v[238:241], v[82:97]
	ds_read_b128 v[234:237], v74 offset:128
	ds_read_b128 v[238:241], v162 offset:17536
	s_waitcnt lgkmcnt(4)
	v_mfma_f32_32x32x16_bf16 v[82:97], v[246:249], v[250:253], v[82:97]
	ds_read_b128 v[246:249], v74 offset:160
	ds_read_b128 v[250:253], v162 offset:17568
	s_waitcnt lgkmcnt(4)
	v_mfma_f32_32x32x16_bf16 v[82:97], v[66:69], v[70:73], v[82:97]
	ds_read_b128 v[66:69], v74 offset:192
	ds_read_b128 v[70:73], v162 offset:17600
	s_waitcnt lgkmcnt(4)
	v_mfma_f32_32x32x16_bf16 v[82:97], v[234:237], v[238:241], v[82:97]
	ds_read_b128 v[234:237], v74 offset:224
	ds_read_b128 v[238:241], v162 offset:17632
	s_waitcnt lgkmcnt(4)
	v_mfma_f32_32x32x16_bf16 v[82:97], v[246:249], v[250:253], v[82:97]
	s_waitcnt lgkmcnt(2)
	v_mfma_f32_32x32x16_bf16 v[82:97], v[66:69], v[70:73], v[82:97]
	s_waitcnt lgkmcnt(0)
	v_mfma_f32_32x32x16_bf16 v[82:97], v[234:237], v[238:241], v[82:97]
.LBB0_2688:
	s_or_b64 exec, exec, s[92:93]
	ds_read2_b64 v[66:69], v157 offset1:2
	v_cvt_pk_bf16_f32 v70, v50, v51
	v_cvt_pk_bf16_f32 v71, v52, v53
	v_cvt_pk_bf16_f32 v72, v54, v55
	v_cvt_pk_bf16_f32 v73, v56, v57
	ds_read2_b64 v[214:217], v157 offset0:4 offset1:6
	ds_read2_b64 v[234:237], v157 offset0:8 offset1:10
	ds_read2_b64 v[238:241], v157 offset0:12 offset1:14
	ds_read2_b64 v[246:249], v157 offset0:16 offset1:18
	v_cvt_pk_bf16_f32 v218, v58, v59
	v_cvt_pk_bf16_f32 v219, v60, v61
	v_cvt_pk_bf16_f32 v220, v62, v63
	s_waitcnt lgkmcnt(4)
	v_mfma_f32_32x32x16_bf16 v[66:81], v[66:69], v[70:73], 0
	v_cvt_pk_bf16_f32 v221, v64, v65
	s_waitcnt lgkmcnt(3)
	s_nop 0
	v_mfma_f32_32x32x16_bf16 v[66:81], v[214:217], v[218:221], v[66:81]
	ds_read2_b64 v[214:217], v157 offset0:20 offset1:22
	v_cvt_pk_bf16_f32 v218, v34, v35
	v_cvt_pk_bf16_f32 v219, v36, v37
	v_cvt_pk_bf16_f32 v220, v38, v39
	v_cvt_pk_bf16_f32 v221, v40, v41
	s_waitcnt lgkmcnt(3)
	s_nop 0
	v_mfma_f32_32x32x16_bf16 v[66:81], v[234:237], v[218:221], v[66:81]
	ds_read2_b64 v[234:237], v157 offset0:24 offset1:26
	v_cvt_pk_bf16_f32 v218, v42, v43
	v_cvt_pk_bf16_f32 v219, v44, v45
	v_cvt_pk_bf16_f32 v220, v46, v47
	v_cvt_pk_bf16_f32 v221, v48, v49
	s_waitcnt lgkmcnt(3)
	s_nop 0
	v_mfma_f32_32x32x16_bf16 v[66:81], v[238:241], v[218:221], v[66:81]
	ds_read2_b64 v[238:241], v157 offset0:28 offset1:30
	v_cvt_pk_bf16_f32 v218, v18, v19
	v_cvt_pk_bf16_f32 v219, v20, v21
	v_cvt_pk_bf16_f32 v220, v22, v23
	v_cvt_pk_bf16_f32 v221, v24, v25
	s_waitcnt lgkmcnt(3)
	s_nop 0
	v_mfma_f32_32x32x16_bf16 v[66:81], v[246:249], v[218:221], v[66:81]
	v_cvt_pk_bf16_f32 v218, v26, v27
	v_cvt_pk_bf16_f32 v219, v28, v29
	v_cvt_pk_bf16_f32 v220, v30, v31
	v_cvt_pk_bf16_f32 v221, v32, v33
	s_waitcnt lgkmcnt(2)
	s_nop 0
	v_mfma_f32_32x32x16_bf16 v[66:81], v[214:217], v[218:221], v[66:81]
	v_cvt_pk_bf16_f32 v218, v2, v3
	v_cvt_pk_bf16_f32 v219, v4, v5
	v_cvt_pk_bf16_f32 v220, v6, v7
	v_cvt_pk_bf16_f32 v221, v8, v9
	s_waitcnt lgkmcnt(1)
	s_nop 0
	v_mfma_f32_32x32x16_bf16 v[66:81], v[234:237], v[218:221], v[66:81]
	v_cvt_pk_bf16_f32 v218, v10, v11
	v_cvt_pk_bf16_f32 v219, v12, v13
	v_cvt_pk_bf16_f32 v220, v14, v15
	v_cvt_pk_bf16_f32 v221, v16, v17
	s_waitcnt lgkmcnt(0)
	s_barrier
	v_mfma_f32_32x32x16_bf16 v[66:81], v[238:241], v[218:221], v[66:81]
	s_and_saveexec_b64 s[92:93], s[4:5]
	s_xor_b64 s[92:93], exec, s[92:93]
	s_cbranch_execz .LBB0_2722
	ds_read_b32 v145, v163
	ds_read_b32 v141, v164
	v_mov_b32_e32 v147, 0
	v_mov_b32_e32 v214, 0
	s_and_saveexec_b64 s[94:95], s[18:19]
	s_cbranch_execz .LBB0_2691
	ds_read_b32 v214, v175
	s_waitcnt lgkmcnt(0)
	v_sub_f32_e32 v214, v214, v145
	v_mul_f32_e32 v214, 0x3fb8aa3b, v214
	v_exp_f32_e32 v214, v214
	s_nop 0
	v_mul_f32_e32 v82, v82, v214
	v_mul_f32_e32 v214, v141, v82
